# hot GEMM loop heads aligned to 64 bytes
# baseline (speedup 1.0000x reference)
.LBB0_329:
	v_mov_b32_e32 v10, v231
	ds_read_b64 v[134:135], v229 offset:63760
	ds_read_b64 v[136:137], v229 offset:63760
	s_ashr_i32 s7, s6, 31
	s_lshl_b64 s[2:3], s[6:7], 18
	v_ashrrev_i32_e32 v4, 3, v10
	v_ashrrev_i32_e32 v5, 31, v4
	v_lshl_add_u64 v[0:1], v[132:133], 0, s[2:3]
	v_lshlrev_b64 v[6:7], 11, v[4:5]
	v_lshlrev_b32_e32 v5, 4, v10
	s_ashr_i32 s1, s0, 31
	v_lshl_add_u64 v[0:1], v[0:1], 0, v[6:7]
	v_and_b32_e32 v228, 0x70, v5
	s_lshl_b64 s[4:5], s[0:1], 18
	v_lshl_add_u64 v[0:1], v[0:1], 0, v[228:229]
	s_mov_b32 s1, 0x10000
	v_add_co_u32_e32 v8, vcc, s1, v0
	v_lshl_add_u64 v[2:3], v[130:131], 0, s[4:5]
	s_nop 0
	v_addc_co_u32_e32 v9, vcc, 0, v1, vcc
	s_mov_b32 s4, 0x20000
	global_load_dwordx4 v[64:67], v[0:1], off
	global_load_dwordx4 v[68:71], v[8:9], off
	v_add_co_u32_e32 v8, vcc, s4, v0
	s_mov_b32 s5, 0x30000
	s_nop 0
	v_addc_co_u32_e32 v9, vcc, 0, v1, vcc
	v_lshl_add_u64 v[2:3], v[2:3], 0, v[6:7]
	v_add_co_u32_e32 v0, vcc, s5, v0
	v_lshl_add_u64 v[138:139], v[2:3], 0, v[228:229]
	s_nop 0
	v_addc_co_u32_e32 v1, vcc, 0, v1, vcc
	global_load_dwordx4 v[72:75], v[8:9], off
	global_load_dwordx4 v[76:79], v[0:1], off
	v_add_co_u32_e32 v0, vcc, s1, v138
	global_load_dwordx4 v[80:83], v[138:139], off
	s_nop 0
	v_addc_co_u32_e32 v1, vcc, 0, v139, vcc
	v_add_co_u32_e32 v2, vcc, s4, v138
	s_movk_i32 s1, 0x90
	s_nop 0
	v_addc_co_u32_e32 v3, vcc, 0, v139, vcc
	global_load_dwordx4 v[84:87], v[0:1], off
	global_load_dwordx4 v[88:91], v[2:3], off
	v_add_co_u32_e32 v0, vcc, s5, v138
	v_mad_u64_u32 v[140:141], s[4:5], v4, s1, v[228:229]
	s_nop 0
	v_addc_co_u32_e32 v1, vcc, 0, v139, vcc
	global_load_dwordx4 v[92:95], v[0:1], off
	v_ashrrev_i32_e32 v0, 1, v10
	v_bfe_u32 v141, v10, 5, 1
	v_and_b32_e32 v146, 0xffffffc0, v0
	v_and_or_b32 v1, v10, 31, v146
	v_lshlrev_b32_e32 v0, 4, v141
	v_mad_u64_u32 v[142:143], s[4:5], v1, s1, v[0:1]
	v_and_b32_e32 v143, 0x5f, v10
	v_mad_u32_u24 v147, v143, s1, v0
	v_lshl_add_u64 v[0:1], s[2:3], 0, v[6:7]
	v_and_b32_e32 v2, 7, v10
	v_lshl_or_b32 v0, v2, 4, v0
	v_lshl_add_u64 v[144:145], v[128:129], 0, v[0:1]
	v_mov_b32_e32 v0, 0
	s_mov_b64 s[2:3], 0
	v_mov_b32_e32 v1, v0
	v_mov_b32_e32 v2, v0
	v_mov_b32_e32 v3, v0
	v_mov_b32_e32 v4, v0
	v_mov_b32_e32 v5, v0
	v_mov_b32_e32 v6, v0
	v_mov_b32_e32 v7, v0
	v_mov_b32_e32 v8, v0
	v_mov_b32_e32 v9, v0
	v_mov_b32_e32 v10, v0
	v_mov_b32_e32 v11, v0
	v_mov_b32_e32 v12, v0
	v_mov_b32_e32 v13, v0
	v_mov_b32_e32 v14, v0
	v_mov_b32_e32 v15, v0
	v_mov_b32_e32 v16, v0
	v_mov_b32_e32 v17, v0
	v_mov_b32_e32 v18, v0
	v_mov_b32_e32 v19, v0
	v_mov_b32_e32 v20, v0
	v_mov_b32_e32 v21, v0
	v_mov_b32_e32 v22, v0
	v_mov_b32_e32 v23, v0
	v_mov_b32_e32 v24, v0
	v_mov_b32_e32 v25, v0
	v_mov_b32_e32 v26, v0
	v_mov_b32_e32 v27, v0
	v_mov_b32_e32 v28, v0
	v_mov_b32_e32 v29, v0
	v_mov_b32_e32 v30, v0
	v_mov_b32_e32 v31, v0
	v_mov_b32_e32 v32, v0
	v_mov_b32_e32 v33, v0
	v_mov_b32_e32 v34, v0
	v_mov_b32_e32 v35, v0
	v_mov_b32_e32 v36, v0
	v_mov_b32_e32 v37, v0
	v_mov_b32_e32 v38, v0
	v_mov_b32_e32 v39, v0
	v_mov_b32_e32 v40, v0
	v_mov_b32_e32 v41, v0
	v_mov_b32_e32 v42, v0
	v_mov_b32_e32 v43, v0
	v_mov_b32_e32 v44, v0
	v_mov_b32_e32 v45, v0
	v_mov_b32_e32 v46, v0
	v_mov_b32_e32 v47, v0
	v_mov_b32_e32 v48, v0
	v_mov_b32_e32 v49, v0
	v_mov_b32_e32 v50, v0
	v_mov_b32_e32 v51, v0
	v_mov_b32_e32 v52, v0
	v_mov_b32_e32 v53, v0
	v_mov_b32_e32 v54, v0
	v_mov_b32_e32 v55, v0
	v_mov_b32_e32 v56, v0
	v_mov_b32_e32 v57, v0
	v_mov_b32_e32 v58, v0
	v_mov_b32_e32 v59, v0
	v_mov_b32_e32 v60, v0
	v_mov_b32_e32 v61, v0
	v_mov_b32_e32 v62, v0
	v_mov_b32_e32 v63, v0
	v_lshrrev_b32_e32 v152, 3, v231
	v_cmp_gt_u32_e32 vcc, 24, v152
	v_mov_b32_e32 v153, 0xebc0
	v_mov_b32_e32 v148, 0xea00
	v_add_u32_e32 v149, 0x10fc0, v140
	v_cndmask_b32_e32 v148, v153, v148, vcc
	v_and_b32_e32 v152, 0x5f, v231
	v_cmp_gt_u32_e32 vcc, 56, v152
	v_mov_b32_e32 v153, 0xd9c0
	v_mov_b32_e32 v150, 0xd800
	v_add_u32_e32 v148, v148, v140
	v_cndmask_b32_e32 v150, v153, v150, vcc
	v_add_u32_e32 v152, 32, v152
	v_cmp_gt_u32_e32 vcc, 56, v152
	v_mov_b32_e32 v151, 0xd800
	v_add_u32_e32 v150, v150, v147
	v_add_u32_e32 v152, 0x1200, v147
	v_cndmask_b32_e32 v151, v153, v151, vcc
	v_add_u32_e32 v151, v151, v152
	v_lshl_add_u64 v[168:169], v[144:145], 0, s[2:3]
	v_add_co_u32_e32 v160, vcc, 0x4ad4000, v168
	v_lshl_add_u64 v[184:185], v[138:139], 0, s[2:3]
	s_nop 0
	v_addc_co_u32_e32 v161, vcc, 0, v169, vcc
	v_add_co_u32_e32 v164, vcc, 0x4ae4000, v168
	s_nop 1
	v_addc_co_u32_e32 v165, vcc, 0, v169, vcc
	v_add_co_u32_e32 v170, vcc, 0x4af4000, v168
	global_load_dwordx4 v[160:163], v[160:161], off offset:128
	s_nop 0
	global_load_dwordx4 v[164:167], v[164:165], off offset:128
	v_addc_co_u32_e32 v171, vcc, 0, v169, vcc
	v_add_co_u32_e32 v172, vcc, 0x4b04000, v168
	s_nop 1
	v_addc_co_u32_e32 v173, vcc, 0, v169, vcc
	v_add_co_u32_e32 v180, vcc, 0x10000, v184
	global_load_dwordx4 v[168:171], v[170:171], off offset:128
	s_nop 0
	global_load_dwordx4 v[172:175], v[172:173], off offset:128
	v_addc_co_u32_e32 v181, vcc, 0, v185, vcc
	v_add_co_u32_e32 v186, vcc, 0x20000, v184
	global_load_dwordx4 v[176:179], v[184:185], off offset:128
	s_nop 0
	global_load_dwordx4 v[180:183], v[180:181], off offset:128
	v_addc_co_u32_e32 v187, vcc, 0, v185, vcc
	v_add_co_u32_e32 v188, vcc, 0x30000, v184
	s_nop 1
	v_addc_co_u32_e32 v189, vcc, 0, v185, vcc
	global_load_dwordx4 v[184:187], v[186:187], off offset:128
	s_nop 0
	global_load_dwordx4 v[188:191], v[188:189], off offset:128
	s_waitcnt vmcnt(8)
	ds_write_b128 v140, v[64:67]
	ds_write_b128 v140, v[68:71] offset:4608
	ds_write_b128 v140, v[72:75] offset:9216
	ds_write_b128 v140, v[76:79] offset:13824
	ds_write_b128 v140, v[80:83] offset:18432
	ds_write_b128 v140, v[84:87] offset:23040
	ds_write_b128 v140, v[88:91] offset:27648
	ds_write_b128 v140, v[92:95] offset:32256
	s_waitcnt lgkmcnt(0)
	s_barrier
	.p2align 6

.LBB0_867:
	s_waitcnt lgkmcnt(5)
	v_mfma_f32_32x32x16_bf16 v[48:63], v[112:115], v[120:123], v[48:63]
	s_waitcnt lgkmcnt(1)
	v_mfma_f32_32x32x16_bf16 v[32:47], v[112:115], v[124:127], v[32:47]
	v_mfma_f32_32x32x16_bf16 v[16:31], v[116:119], v[120:123], v[16:31]
	v_mfma_f32_32x32x16_bf16 v[0:15], v[116:119], v[124:127], v[0:15]
	ds_read_b128 v[112:115], v132 offset:64
	ds_read_b128 v[116:119], v132 offset:4672
	ds_read_b128 v[120:123], v151 offset:18496
	ds_read_b128 v[124:127], v151 offset:23104
	v_mfma_f32_32x32x16_bf16 v[48:63], v[96:99], v[100:103], v[48:63]
	s_waitcnt lgkmcnt(4)
	v_mfma_f32_32x32x16_bf16 v[32:47], v[96:99], v[108:111], v[32:47]
	v_mfma_f32_32x32x16_bf16 v[16:31], v[104:107], v[100:103], v[16:31]
	v_mfma_f32_32x32x16_bf16 v[0:15], v[104:107], v[108:111], v[0:15]
	ds_read_b128 v[96:99], v132 offset:96
	ds_read_b128 v[100:103], v132 offset:4704
	ds_read_b128 v[104:107], v151 offset:18528
	ds_read_b128 v[108:111], v151 offset:23136
	s_waitcnt lgkmcnt(5)
	v_mfma_f32_32x32x16_bf16 v[48:63], v[112:115], v[120:123], v[48:63]
	s_waitcnt lgkmcnt(4)
	v_mfma_f32_32x32x16_bf16 v[32:47], v[112:115], v[124:127], v[32:47]
	v_mfma_f32_32x32x16_bf16 v[16:31], v[116:119], v[120:123], v[16:31]
	v_mfma_f32_32x32x16_bf16 v[0:15], v[116:119], v[124:127], v[0:15]
	s_waitcnt lgkmcnt(1)
	v_mfma_f32_32x32x16_bf16 v[48:63], v[96:99], v[104:107], v[48:63]
	s_waitcnt lgkmcnt(0)
	v_mfma_f32_32x32x16_bf16 v[32:47], v[96:99], v[108:111], v[32:47]
	v_mfma_f32_32x32x16_bf16 v[16:31], v[100:103], v[104:107], v[16:31]
	v_mfma_f32_32x32x16_bf16 v[0:15], v[100:103], v[108:111], v[0:15]
	s_add_u32 s4, s4, 0x80
	s_addc_u32 s5, s5, 0
	s_add_i32 s14, s14, 1
	s_cmp_lg_u32 s6, s4
	s_cbranch_scc0 .LBB0_835
	.p2align 6

.LBB0_1591:
	ds_read_b64 v[134:135], v229 offset:63760
	ds_read_b64 v[132:133], v229 offset:63760
	ds_read_b128 v[64:67], v229 offset:63488
	ds_read_b64 v[0:1], v229 offset:63760
	ds_read_b64 v[2:3], v229 offset:63760
	v_mov_b32_e32 v14, v231
	s_ashr_i32 s39, s38, 31
	v_ashrrev_i32_e32 v8, 3, v14
	v_ashrrev_i32_e32 v9, 31, v8
	s_lshl_b64 s[4:5], s[38:39], 18
	v_lshlrev_b64 v[10:11], 11, v[8:9]
	v_lshlrev_b32_e32 v9, 4, v14
	s_waitcnt lgkmcnt(0)
	v_lshl_add_u64 v[6:7], v[2:3], 0, s[4:5]
	v_and_b32_e32 v228, 0x70, v9
	s_movk_i32 s6, 0x90
	v_lshl_add_u64 v[6:7], v[6:7], 0, v[10:11]
	v_mad_u64_u32 v[136:137], s[2:3], v8, s6, v[228:229]
	v_lshl_add_u64 v[6:7], v[6:7], 0, v[228:229]
	s_mov_b32 s2, 0x530000
	v_add_co_u32_e32 v8, vcc, s2, v6
	s_mov_b32 s2, 0x520000
	s_nop 0
	v_addc_co_u32_e32 v9, vcc, 0, v7, vcc
	v_add_co_u32_e32 v12, vcc, s2, v6
	s_ashr_i32 s41, s40, 31
	s_nop 0
	v_addc_co_u32_e32 v13, vcc, 0, v7, vcc
	s_mov_b32 s2, 0x510000
	s_lshl_b64 s[0:1], s[40:41], 18
	global_load_dwordx4 v[68:71], v[8:9], off
	global_load_dwordx4 v[72:75], v[12:13], off
	v_add_co_u32_e32 v8, vcc, s2, v6
	v_lshl_add_u64 v[4:5], v[0:1], 0, s[0:1]
	s_nop 0
	v_addc_co_u32_e32 v9, vcc, 0, v7, vcc
	s_mov_b32 s2, 0x500000
	v_lshl_add_u64 v[4:5], v[4:5], 0, v[10:11]
	v_add_co_u32_e32 v6, vcc, s2, v6
	v_lshl_add_u64 v[4:5], v[4:5], 0, v[228:229]
	s_nop 0
	v_addc_co_u32_e32 v7, vcc, 0, v7, vcc
	s_mov_b32 s2, 0x4b04000
	global_load_dwordx4 v[76:79], v[8:9], off
	global_load_dwordx4 v[80:83], v[6:7], off
	v_add_co_u32_e32 v6, vcc, s2, v4
	s_mov_b32 s2, 0x4af4000
	s_nop 0
	v_addc_co_u32_e32 v7, vcc, 0, v5, vcc
	v_add_co_u32_e32 v8, vcc, s2, v4
	s_mov_b32 s2, 0x4ae4000
	s_nop 0
	v_addc_co_u32_e32 v9, vcc, 0, v5, vcc
	global_load_dwordx4 v[84:87], v[6:7], off
	global_load_dwordx4 v[88:91], v[8:9], off
	v_add_co_u32_e32 v6, vcc, s2, v4
	s_mov_b32 s2, 0x4ad4000
	s_nop 0
	v_addc_co_u32_e32 v7, vcc, 0, v5, vcc
	v_add_co_u32_e32 v4, vcc, s2, v4
	v_ashrrev_i32_e32 v15, 1, v14
	s_nop 0
	v_addc_co_u32_e32 v5, vcc, 0, v5, vcc
	global_load_dwordx4 v[92:95], v[6:7], off
	global_load_dwordx4 v[96:99], v[4:5], off
	v_bfe_u32 v144, v14, 5, 1
	v_and_b32_e32 v137, 0xffffffc0, v15
	v_and_or_b32 v5, v14, 31, v137
	v_lshlrev_b32_e32 v4, 4, v144
	v_mad_u64_u32 v[138:139], s[2:3], v5, s6, v[4:5]
	v_and_b32_e32 v139, 0x5f, v14
	v_mad_u32_u24 v145, v139, s6, v4
	v_lshl_add_u64 v[4:5], s[4:5], 0, v[10:11]
	v_or_b32_e32 v4, v4, v228
	v_lshl_add_u64 v[140:141], v[2:3], 0, v[4:5]
	v_lshl_add_u64 v[2:3], s[0:1], 0, v[10:11]
	v_or_b32_e32 v2, v2, v228
	v_lshl_add_u64 v[142:143], v[0:1], 0, v[2:3]
	v_mov_b32_e32 v0, 0
	s_mov_b32 s2, 0
	s_mov_b64 s[0:1], 0
	v_mov_b32_e32 v1, v0
	v_mov_b32_e32 v2, v0
	v_mov_b32_e32 v3, v0
	v_mov_b32_e32 v4, v0
	v_mov_b32_e32 v5, v0
	v_mov_b32_e32 v6, v0
	v_mov_b32_e32 v7, v0
	v_mov_b32_e32 v8, v0
	v_mov_b32_e32 v9, v0
	v_mov_b32_e32 v10, v0
	v_mov_b32_e32 v11, v0
	v_mov_b32_e32 v12, v0
	v_mov_b32_e32 v13, v0
	v_mov_b32_e32 v14, v0
	v_mov_b32_e32 v15, v0
	v_mov_b32_e32 v16, v0
	v_mov_b32_e32 v17, v0
	v_mov_b32_e32 v18, v0
	v_mov_b32_e32 v19, v0
	v_mov_b32_e32 v20, v0
	v_mov_b32_e32 v21, v0
	v_mov_b32_e32 v22, v0
	v_mov_b32_e32 v23, v0
	v_mov_b32_e32 v24, v0
	v_mov_b32_e32 v25, v0
	v_mov_b32_e32 v26, v0
	v_mov_b32_e32 v27, v0
	v_mov_b32_e32 v28, v0
	v_mov_b32_e32 v29, v0
	v_mov_b32_e32 v30, v0
	v_mov_b32_e32 v31, v0
	v_mov_b32_e32 v32, v0
	v_mov_b32_e32 v33, v0
	v_mov_b32_e32 v34, v0
	v_mov_b32_e32 v35, v0
	v_mov_b32_e32 v36, v0
	v_mov_b32_e32 v37, v0
	v_mov_b32_e32 v38, v0
	v_mov_b32_e32 v39, v0
	v_mov_b32_e32 v40, v0
	v_mov_b32_e32 v41, v0
	v_mov_b32_e32 v42, v0
	v_mov_b32_e32 v43, v0
	v_mov_b32_e32 v44, v0
	v_mov_b32_e32 v45, v0
	v_mov_b32_e32 v46, v0
	v_mov_b32_e32 v47, v0
	v_mov_b32_e32 v48, v0
	v_mov_b32_e32 v49, v0
	v_mov_b32_e32 v50, v0
	v_mov_b32_e32 v51, v0
	v_mov_b32_e32 v52, v0
	v_mov_b32_e32 v53, v0
	v_mov_b32_e32 v54, v0
	v_mov_b32_e32 v55, v0
	v_mov_b32_e32 v56, v0
	v_mov_b32_e32 v57, v0
	v_mov_b32_e32 v58, v0
	v_mov_b32_e32 v59, v0
	v_mov_b32_e32 v60, v0
	v_mov_b32_e32 v61, v0
	v_mov_b32_e32 v62, v0
	v_mov_b32_e32 v63, v0
	v_lshrrev_b32_e32 v163, 3, v231
	v_cmp_gt_u32_e32 vcc, 24, v163
	v_mov_b32_e32 v164, 0xebc0
	v_mov_b32_e32 v159, 0xea00
	v_add_u32_e32 v160, 0x10fc0, v136
	v_cndmask_b32_e32 v159, v164, v159, vcc
	v_and_b32_e32 v163, 0x5f, v231
	v_cmp_gt_u32_e32 vcc, 56, v163
	v_mov_b32_e32 v164, 0xd9c0
	v_mov_b32_e32 v161, 0xd800
	v_add_u32_e32 v159, v159, v136
	v_cndmask_b32_e32 v161, v164, v161, vcc
	v_add_u32_e32 v163, 32, v163
	v_cmp_gt_u32_e32 vcc, 56, v163
	v_mov_b32_e32 v162, 0xd800
	v_add_u32_e32 v161, v161, v145
	v_add_u32_e32 v163, 0x1200, v145
	v_cndmask_b32_e32 v162, v164, v162, vcc
	v_add_u32_e32 v162, v162, v163
	v_lshl_add_u64 v[168:169], v[142:143], 0, s[0:1]
	v_add_co_u32_e32 v170, vcc, 0x4ad4000, v168
	s_nop 1
	v_addc_co_u32_e32 v171, vcc, 0, v169, vcc
	v_add_co_u32_e32 v172, vcc, 0x4ae4000, v168
	s_nop 1
	v_addc_co_u32_e32 v173, vcc, 0, v169, vcc
	global_load_dwordx4 v[196:199], v[170:171], off offset:128
	global_load_dwordx4 v[192:195], v[172:173], off offset:128
	v_add_co_u32_e32 v170, vcc, 0x4af4000, v168
	s_nop 1
	v_addc_co_u32_e32 v171, vcc, 0, v169, vcc
	v_add_co_u32_e32 v168, vcc, 0x4b04000, v168
	s_nop 1
	v_addc_co_u32_e32 v169, vcc, 0, v169, vcc
	global_load_dwordx4 v[188:191], v[170:171], off offset:128
	global_load_dwordx4 v[184:187], v[168:169], off offset:128
	v_lshl_add_u64 v[168:169], v[140:141], 0, s[0:1]
	v_add_co_u32_e32 v170, vcc, 0x500000, v168
	s_nop 1
	v_addc_co_u32_e32 v171, vcc, 0, v169, vcc
	v_add_co_u32_e32 v172, vcc, 0x510000, v168
	s_nop 1
	v_addc_co_u32_e32 v173, vcc, 0, v169, vcc
	global_load_dwordx4 v[180:183], v[170:171], off offset:128
	global_load_dwordx4 v[176:179], v[172:173], off offset:128
	v_add_co_u32_e32 v170, vcc, 0x520000, v168
	s_nop 1
	v_addc_co_u32_e32 v171, vcc, 0, v169, vcc
	v_add_co_u32_e32 v168, vcc, 0x530000, v168
	s_nop 1
	v_addc_co_u32_e32 v169, vcc, 0, v169, vcc
	global_load_dwordx4 v[172:175], v[170:171], off offset:128
	s_nop 0
	global_load_dwordx4 v[168:171], v[168:169], off offset:128
	s_waitcnt vmcnt(8)
	ds_write_b128 v136, v[96:99]
	ds_write_b128 v136, v[92:95] offset:4608
	ds_write_b128 v136, v[88:91] offset:9216
	ds_write_b128 v136, v[84:87] offset:13824
	ds_write_b128 v136, v[80:83] offset:18432
	ds_write_b128 v136, v[76:79] offset:23040
	ds_write_b128 v136, v[72:75] offset:27648
	ds_write_b128 v136, v[68:71] offset:32256
	s_waitcnt lgkmcnt(0)
	s_barrier
	.p2align 6

.LBB0_2193:
	s_waitcnt lgkmcnt(9)
	v_mfma_f32_32x32x16_bf16 v[112:127], v[208:211], v[204:207], v[112:127]
	s_waitcnt lgkmcnt(1)
	v_mfma_f32_32x32x16_bf16 v[96:111], v[208:211], v[220:223], v[96:111]
	v_mfma_f32_32x32x16_bf16 v[80:95], v[224:227], v[204:207], v[80:95]
	v_mfma_f32_32x32x16_bf16 v[64:79], v[224:227], v[220:223], v[64:79]
	v_mfma_f32_32x32x16_bf16 v[48:63], v[216:219], v[204:207], v[48:63]
	v_mfma_f32_32x32x16_bf16 v[32:47], v[216:219], v[220:223], v[32:47]
	v_mfma_f32_32x32x16_bf16 v[16:31], v[212:215], v[204:207], v[16:31]
	v_mfma_f32_32x32x16_bf16 v[0:15], v[212:215], v[220:223], v[0:15]
	ds_read_b128 v[204:207], v236 offset:64
	ds_read_b128 v[208:211], v236 offset:4672
	ds_read_b128 v[212:215], v236 offset:9280
	ds_read_b128 v[216:219], v236 offset:13888
	ds_read_b128 v[220:223], v235 offset:36928
	ds_read_b128 v[224:227], v235 offset:41536
	v_mfma_f32_32x32x16_bf16 v[112:127], v[184:187], v[180:183], v[112:127]
	s_waitcnt lgkmcnt(6)
	v_mfma_f32_32x32x16_bf16 v[96:111], v[184:187], v[196:199], v[96:111]
	v_mfma_f32_32x32x16_bf16 v[80:95], v[200:203], v[180:183], v[80:95]
	v_mfma_f32_32x32x16_bf16 v[64:79], v[200:203], v[196:199], v[64:79]
	v_mfma_f32_32x32x16_bf16 v[48:63], v[192:195], v[180:183], v[48:63]
	v_mfma_f32_32x32x16_bf16 v[32:47], v[192:195], v[196:199], v[32:47]
	v_mfma_f32_32x32x16_bf16 v[16:31], v[188:191], v[180:183], v[16:31]
	v_mfma_f32_32x32x16_bf16 v[0:15], v[188:191], v[196:199], v[0:15]
	ds_read_b128 v[180:183], v236 offset:96
	ds_read_b128 v[184:187], v236 offset:4704
	ds_read_b128 v[188:191], v236 offset:9312
	ds_read_b128 v[192:195], v236 offset:13920
	ds_read_b128 v[196:199], v235 offset:36960
	ds_read_b128 v[200:203], v235 offset:41568
	s_waitcnt lgkmcnt(7)
	v_mfma_f32_32x32x16_bf16 v[112:127], v[204:207], v[220:223], v[112:127]
	s_waitcnt lgkmcnt(6)
	v_mfma_f32_32x32x16_bf16 v[96:111], v[204:207], v[224:227], v[96:111]
	v_mfma_f32_32x32x16_bf16 v[80:95], v[208:211], v[220:223], v[80:95]
	v_mfma_f32_32x32x16_bf16 v[64:79], v[208:211], v[224:227], v[64:79]
	v_mfma_f32_32x32x16_bf16 v[48:63], v[212:215], v[220:223], v[48:63]
	v_mfma_f32_32x32x16_bf16 v[32:47], v[212:215], v[224:227], v[32:47]
	v_mfma_f32_32x32x16_bf16 v[16:31], v[216:219], v[220:223], v[16:31]
	v_mfma_f32_32x32x16_bf16 v[0:15], v[216:219], v[224:227], v[0:15]
	s_waitcnt lgkmcnt(1)
	v_mfma_f32_32x32x16_bf16 v[112:127], v[180:183], v[196:199], v[112:127]
	s_waitcnt lgkmcnt(0)
	v_mfma_f32_32x32x16_bf16 v[96:111], v[180:183], v[200:203], v[96:111]
	v_mfma_f32_32x32x16_bf16 v[80:95], v[184:187], v[196:199], v[80:95]
	v_mfma_f32_32x32x16_bf16 v[64:79], v[184:187], v[200:203], v[64:79]
	v_mfma_f32_32x32x16_bf16 v[48:63], v[188:191], v[196:199], v[48:63]
	v_mfma_f32_32x32x16_bf16 v[32:47], v[188:191], v[200:203], v[32:47]
	v_mfma_f32_32x32x16_bf16 v[16:31], v[192:195], v[196:199], v[16:31]
	v_mfma_f32_32x32x16_bf16 v[0:15], v[192:195], v[200:203], v[0:15]
	s_add_u32 s2, s2, 0x80
	s_addc_u32 s3, s3, 0
	s_cmpk_eq_i32 s2, 0x800
	s_cbranch_scc1 .LBB0_2196
	.p2align 6

.LBB0_2262:
	s_mov_b64 s[2:3], -1
	s_and_b64 vcc, exec, s[0:1]
	s_cbranch_vccz .LBB0_2254
	s_ashr_i32 s0, s6, 31
	ds_read_b64 v[128:129], v229 offset:63760
	ds_read_b64 v[130:131], v229 offset:63760
	ds_read_b64 v[0:1], v229 offset:63760
	s_lshr_b32 s0, s0, 29
	s_add_i32 s0, s6, s0
	s_and_b32 s0, s0, -8
	ds_read_b64 v[2:3], v229 offset:63760
	s_sub_i32 s2, s6, s0
	s_mul_hi_i32 s1, s5, 0xb0000
	s_mul_i32 s0, s5, 0xb0000
	s_waitcnt lgkmcnt(0)
	v_lshl_add_u64 v[4:5], v[0:1], 0, s[0:1]
	s_mov_b64 s[0:1], 0xb2d4000
	v_lshl_add_u64 v[4:5], v[4:5], 0, s[0:1]
	s_mul_i32 s0, s2, 0xb0000
	s_ashr_i32 s1, s0, 31
	v_lshl_add_u64 v[2:3], v[2:3], 0, s[0:1]
	v_mov_b32_e32 v14, v231
	v_lshl_add_u64 v[6:7], v[2:3], 0, s[54:55]
	s_movk_i32 s3, 0x90
	v_ashrrev_i32_e32 v15, 3, v14
	v_lshlrev_b32_e32 v8, 4, v14
	v_and_b32_e32 v228, 0x70, v8
	v_mad_i64_i32 v[6:7], s[0:1], v15, s46, v[6:7]
	v_lshl_add_u64 v[6:7], v[6:7], 0, v[228:229]
	v_mad_u64_u32 v[132:133], s[0:1], v15, s3, v[228:229]
	v_ashrrev_i32_e32 v8, 1, v14
	v_and_b32_e32 v133, 0xffffffc0, v8
	v_add_co_u32_e32 v8, vcc, s47, v6
	v_mad_i64_i32 v[4:5], s[0:1], v15, s46, v[4:5]
	s_nop 0
	v_addc_co_u32_e32 v9, vcc, 0, v7, vcc
	v_add_co_u32_e32 v10, vcc, s48, v6
	v_lshl_add_u64 v[4:5], v[4:5], 0, v[228:229]
	s_nop 0
	v_addc_co_u32_e32 v11, vcc, 0, v7, vcc
	v_add_co_u32_e32 v12, vcc, s49, v6
	v_bfe_u32 v140, v14, 5, 1
	s_nop 0
	v_addc_co_u32_e32 v13, vcc, 0, v7, vcc
	global_load_dwordx4 v[88:91], v[10:11], off
	global_load_dwordx4 v[84:87], v[12:13], off
	global_load_dwordx4 v[92:95], v[8:9], off
	global_load_dwordx4 v[80:83], v[6:7], off
	v_add_co_u32_e32 v6, vcc, s47, v4
	v_and_or_b32 v16, v14, 31, v133
	s_nop 0
	v_addc_co_u32_e32 v7, vcc, 0, v5, vcc
	v_add_co_u32_e32 v8, vcc, s48, v4
	s_nop 1
	v_addc_co_u32_e32 v9, vcc, 0, v5, vcc
	global_load_dwordx4 v[72:75], v[6:7], off
	global_load_dwordx4 v[76:79], v[8:9], off
	v_add_co_u32_e32 v6, vcc, s49, v4
	s_nop 1
	v_addc_co_u32_e32 v7, vcc, 0, v5, vcc
	global_load_dwordx4 v[68:71], v[6:7], off
	global_load_dwordx4 v[64:67], v[4:5], off
	v_lshlrev_b32_e32 v4, 4, v140
	v_mad_u64_u32 v[134:135], s[0:1], v16, s3, v[4:5]
	v_and_b32_e32 v135, 0x5f, v14
	v_mad_u32_u24 v141, v135, s3, v4
	v_mad_i64_i32 v[4:5], s[0:1], v15, s46, 0
	v_and_b32_e32 v6, 7, v14
	v_lshl_or_b32 v4, v6, 4, v4
	v_lshl_add_u64 v[136:137], v[2:3], 0, v[4:5]
	v_mad_i64_i32 v[2:3], s[0:1], s5, v251, v[4:5]
	v_lshl_add_u64 v[138:139], v[0:1], 0, v[2:3]
	v_mov_b32_e32 v0, 0
	s_mov_b32 s3, 0
	s_mov_b64 s[0:1], 0
	v_mov_b32_e32 v1, v0
	v_mov_b32_e32 v2, v0
	v_mov_b32_e32 v3, v0
	v_mov_b32_e32 v4, v0
	v_mov_b32_e32 v5, v0
	v_mov_b32_e32 v6, v0
	v_mov_b32_e32 v7, v0
	v_mov_b32_e32 v8, v0
	v_mov_b32_e32 v9, v0
	v_mov_b32_e32 v10, v0
	v_mov_b32_e32 v11, v0
	v_mov_b32_e32 v12, v0
	v_mov_b32_e32 v13, v0
	v_mov_b32_e32 v14, v0
	v_mov_b32_e32 v15, v0
	v_mov_b32_e32 v16, v0
	v_mov_b32_e32 v17, v0
	v_mov_b32_e32 v18, v0
	v_mov_b32_e32 v19, v0
	v_mov_b32_e32 v20, v0
	v_mov_b32_e32 v21, v0
	v_mov_b32_e32 v22, v0
	v_mov_b32_e32 v23, v0
	v_mov_b32_e32 v24, v0
	v_mov_b32_e32 v25, v0
	v_mov_b32_e32 v26, v0
	v_mov_b32_e32 v27, v0
	v_mov_b32_e32 v28, v0
	v_mov_b32_e32 v29, v0
	v_mov_b32_e32 v30, v0
	v_mov_b32_e32 v31, v0
	v_mov_b32_e32 v32, v0
	v_mov_b32_e32 v33, v0
	v_mov_b32_e32 v34, v0
	v_mov_b32_e32 v35, v0
	v_mov_b32_e32 v36, v0
	v_mov_b32_e32 v37, v0
	v_mov_b32_e32 v38, v0
	v_mov_b32_e32 v39, v0
	v_mov_b32_e32 v40, v0
	v_mov_b32_e32 v41, v0
	v_mov_b32_e32 v42, v0
	v_mov_b32_e32 v43, v0
	v_mov_b32_e32 v44, v0
	v_mov_b32_e32 v45, v0
	v_mov_b32_e32 v46, v0
	v_mov_b32_e32 v47, v0
	v_mov_b32_e32 v48, v0
	v_mov_b32_e32 v49, v0
	v_mov_b32_e32 v50, v0
	v_mov_b32_e32 v51, v0
	v_mov_b32_e32 v52, v0
	v_mov_b32_e32 v53, v0
	v_mov_b32_e32 v54, v0
	v_mov_b32_e32 v55, v0
	v_mov_b32_e32 v56, v0
	v_mov_b32_e32 v57, v0
	v_mov_b32_e32 v58, v0
	v_mov_b32_e32 v59, v0
	v_mov_b32_e32 v60, v0
	v_mov_b32_e32 v61, v0
	v_mov_b32_e32 v62, v0
	v_mov_b32_e32 v63, v0
	v_lshl_add_u64 v[168:169], v[138:139], 0, s[0:1]
	v_add_co_u32_e32 v160, vcc, 0xb2d4000, v168
	v_lshl_add_u64 v[184:185], v[136:137], 0, s[0:1]
	s_nop 0
	v_addc_co_u32_e32 v161, vcc, 0, v169, vcc
	v_add_co_u32_e32 v164, vcc, 0xb300000, v168
	s_nop 1
	v_addc_co_u32_e32 v165, vcc, 0, v169, vcc
	v_add_co_u32_e32 v170, vcc, 0xb32c000, v168
	global_load_dwordx4 v[160:163], v[160:161], off offset:128
	s_nop 0
	global_load_dwordx4 v[164:167], v[164:165], off offset:128
	v_addc_co_u32_e32 v171, vcc, 0, v169, vcc
	v_add_co_u32_e32 v168, vcc, 0xb358000, v168
	s_nop 1
	v_addc_co_u32_e32 v169, vcc, 0, v169, vcc
	v_add_co_u32_e32 v176, vcc, 0x1200000, v184
	global_load_dwordx4 v[172:175], v[170:171], off offset:128
	s_nop 0
	global_load_dwordx4 v[168:171], v[168:169], off offset:128
	v_addc_co_u32_e32 v177, vcc, 0, v185, vcc
	v_add_co_u32_e32 v180, vcc, 0x122c000, v184
	s_nop 1
	v_addc_co_u32_e32 v181, vcc, 0, v185, vcc
	v_add_co_u32_e32 v186, vcc, 0x1258000, v184
	global_load_dwordx4 v[176:179], v[176:177], off offset:128
	s_nop 0
	global_load_dwordx4 v[180:183], v[180:181], off offset:128
	v_addc_co_u32_e32 v187, vcc, 0, v185, vcc
	v_add_co_u32_e32 v188, vcc, 0x1284000, v184
	s_nop 1
	v_addc_co_u32_e32 v189, vcc, 0, v185, vcc
	global_load_dwordx4 v[184:187], v[186:187], off offset:128
	s_nop 0
	global_load_dwordx4 v[188:191], v[188:189], off offset:128
	s_branch .Lgd_even
	.p2align 6
